# retention block second key tile: K fragments for S^T read three steps ahead through two extra buffers instead of 16 serial read-wait-use round trips per half
# baseline (speedup 1.0000x reference)
; template <int NF, int RB>
; __device__ __forceinline__ void qkt1(f32x16& p, const char* Kt, int r32, int hi, const bf16x8* qr) {
; #pragma unroll
;     for (int r = 0; r < 16; ++r) p[r] = 0.f;
;     const char* kb[4];
; #pragma unroll
;     for (int dd = 0; dd < 4; ++dd) kb[dd] = Kt + r32 * RB + (((dd * 16 + hi * 8) * 2) ^ ((r32 & 7) << 4));
; #pragma unroll
;     for (int d0 = 0; d0 < NF; ++d0) { const bf16x8 b0 = *reinterpret_cast<const bf16x8*>(kb[d0 & 3] + (d0 >> 2) * 128);
;         p = __builtin_amdgcn_mfma_f32_32x32x16_bf16(b0, qr[d0], p, 0, 0, 0); }
; }
; __device__ __forceinline__ void ret_block(const bf16_t* __restrict__ proj, const bf16_t* __restrict__ state, bf16_t* __restrict__ mixed, int b, int h, int qb, char* lds) {
;     ...
;             { f32x16 p; qkt1<16, 512>(p, K_lds + buf * SHM, r32, hi, qr);
;               if (diag) {
; #pragma unroll
;                   for (int r = 0; r < 16; ++r) { const int C = (r & 3) + 8 * (r >> 2); if (dq - C < 0) p[r] = 0.f; } }
;               FA_PK4(p, 0, pa0); FA_PK4(p, 8, pa1); }
.LBB0_482:
	s_barrier
	s_cmp_lt_u32 s51, 64
	s_cbranch_scc1 .LBB0_484
	v_or_b32_e32 v64, 64, v191
	s_add_i32 s0, 0, 0x18000
	v_sub_u32_e32 v201, v68, v64
	v_add_u32_e32 v64, s0, v198
	v_add_u32_e32 v148, v64, v196
	v_add_u32_e32 v149, v64, v197
	v_add_u32_e32 v150, v64, v199
	v_add_u32_e32 v151, v64, v200
	ds_read_b128 v[64:67], v148
	ds_read_b128 v[144:147], v149
	ds_read_b128 v[246:249], v150
	ds_read_b128 v[250:253], v151
	v_cmp_gt_i32_e32 vcc, 27, v201
	v_cmp_gt_i32_e64 s[0:1], 26, v201
	s_waitcnt lgkmcnt(3)
	v_mfma_f32_32x32x16_bf16 v[64:79], v[64:67], v[140:143], 0
	v_cmp_gt_i32_e64 s[4:5], 25, v201
	s_and_b64 s[0:1], vcc, s[0:1]
	v_cmp_gt_i32_e64 s[6:7], 24, v201
	v_cmp_gt_i32_e64 s[8:9], 19, v201
	v_cmp_gt_i32_e64 s[10:11], 18, v201
	v_cmp_gt_i32_e64 s[12:13], 17, v201
	v_cmp_gt_i32_e64 s[14:15], 16, v201
	s_waitcnt lgkmcnt(2)
	v_mfma_f32_32x32x16_bf16 v[64:79], v[144:147], v[136:139], v[64:79]
	ds_read_b128 v[144:147], v148 offset:128
	v_cmp_gt_i32_e64 s[16:17], 11, v201
	v_cmp_gt_i32_e64 s[18:19], 10, v201
	v_cmp_gt_i32_e64 s[20:21], 9, v201
	v_cmp_gt_i32_e64 s[22:23], 8, v201
	v_cmp_gt_i32_e64 s[24:25], 3, v201
	v_cmp_gt_i32_e64 s[26:27], 2, v201
	s_waitcnt lgkmcnt(2)
	v_mfma_f32_32x32x16_bf16 v[64:79], v[246:249], v[132:135], v[64:79]
	ds_read_b128 v[246:249], v149 offset:128
	v_cmp_gt_i32_e64 s[28:29], 1, v201
	v_cmp_gt_i32_e64 s[30:31], 0, v201
	s_waitcnt lgkmcnt(2)
	v_mfma_f32_32x32x16_bf16 v[64:79], v[250:253], v[128:131], v[64:79]
	ds_read_b128 v[250:253], v150 offset:128
	s_waitcnt lgkmcnt(2)
	v_mfma_f32_32x32x16_bf16 v[64:79], v[144:147], v[124:127], v[64:79]
	ds_read_b128 v[144:147], v151 offset:128
	s_waitcnt lgkmcnt(2)
	v_mfma_f32_32x32x16_bf16 v[64:79], v[246:249], v[120:123], v[64:79]
	ds_read_b128 v[246:249], v148 offset:256
	s_waitcnt lgkmcnt(2)
	v_mfma_f32_32x32x16_bf16 v[64:79], v[250:253], v[116:119], v[64:79]
	ds_read_b128 v[250:253], v149 offset:256
	s_waitcnt lgkmcnt(2)
	v_mfma_f32_32x32x16_bf16 v[64:79], v[144:147], v[112:115], v[64:79]
	ds_read_b128 v[144:147], v150 offset:256
	s_waitcnt lgkmcnt(2)
	v_mfma_f32_32x32x16_bf16 v[64:79], v[246:249], v[108:111], v[64:79]
	ds_read_b128 v[246:249], v151 offset:256
	s_waitcnt lgkmcnt(2)
	v_mfma_f32_32x32x16_bf16 v[64:79], v[250:253], v[104:107], v[64:79]
	ds_read_b128 v[250:253], v148 offset:384
	s_waitcnt lgkmcnt(2)
	v_mfma_f32_32x32x16_bf16 v[64:79], v[144:147], v[100:103], v[64:79]
	ds_read_b128 v[144:147], v149 offset:384
	s_waitcnt lgkmcnt(2)
	v_mfma_f32_32x32x16_bf16 v[64:79], v[246:249], v[96:99], v[64:79]
	ds_read_b128 v[246:249], v150 offset:384
	s_waitcnt lgkmcnt(2)
	v_mfma_f32_32x32x16_bf16 v[64:79], v[250:253], v[92:95], v[64:79]
	ds_read_b128 v[250:253], v151 offset:384
	s_waitcnt lgkmcnt(2)
	v_mfma_f32_32x32x16_bf16 v[64:79], v[144:147], v[88:91], v[64:79]
	s_waitcnt lgkmcnt(1)
	v_mfma_f32_32x32x16_bf16 v[64:79], v[246:249], v[84:87], v[64:79]
	s_waitcnt lgkmcnt(0)
	v_mfma_f32_32x32x16_bf16 v[64:79], v[250:253], v[80:83], v[64:79]


; template <int NF, int RB>
; __device__ __forceinline__ void qkt1(f32x16& p, const char* Kt, int r32, int hi, const bf16x8* qr) {
; #pragma unroll
;     for (int r = 0; r < 16; ++r) p[r] = 0.f;
;     const char* kb[4];
; #pragma unroll
;     for (int dd = 0; dd < 4; ++dd) kb[dd] = Kt + r32 * RB + (((dd * 16 + hi * 8) * 2) ^ ((r32 & 7) << 4));
; #pragma unroll
;     for (int d0 = 0; d0 < NF; ++d0) { const bf16x8 b0 = *reinterpret_cast<const bf16x8*>(kb[d0 & 3] + (d0 >> 2) * 128);
;         p = __builtin_amdgcn_mfma_f32_32x32x16_bf16(b0, qr[d0], p, 0, 0, 0); }
; }
; __device__ __forceinline__ void ret_block(const bf16_t* __restrict__ proj, const bf16_t* __restrict__ state, bf16_t* __restrict__ mixed, int b, int h, int qb, char* lds) {
;     ...
;             { f32x16 p; qkt1<16, 512>(p, K_lds + buf * SHM, r32, hi, qr);
;               if (diag) {
; #pragma unroll
;                   for (int r = 0; r < 16; ++r) { const int C = (r & 3) + 8 * (r >> 2); if (dq - C < 0) p[r] = 0.f; } }
;               FA_PK4(p, 0, pa0); FA_PK4(p, 8, pa1); }
;             { f32x16 p; qkt1<16, 512>(p, K_lds + buf * SHM + 32 * 512, r32, hi, qr);
;               if (diag) {
; #pragma unroll
;                   for (int r = 0; r < 16; ++r) { const int C = (r & 3) + 8 * (r >> 2) + 32; if (dq - C < 0) p[r] = 0.f; } }
;               FA_PK4(p, 0, pa2); FA_PK4(p, 8, pa3); }
	s_nop 11
	v_cndmask_b32_e64 v78, v78, 0, s[0:1]
	s_and_b64 s[0:1], s[0:1], s[4:5]
	s_and_b64 s[4:5], s[0:1], s[6:7]
	v_cndmask_b32_e64 v77, v77, 0, s[0:1]
	s_and_b64 s[0:1], s[4:5], s[8:9]
	v_cndmask_b32_e64 v76, v76, 0, s[4:5]
	s_and_b64 s[4:5], s[0:1], s[10:11]
	v_cndmask_b32_e64 v75, v75, 0, s[0:1]
	s_and_b64 s[0:1], s[4:5], s[12:13]
	v_cndmask_b32_e64 v74, v74, 0, s[4:5]
	s_and_b64 s[4:5], s[0:1], s[14:15]
	v_cndmask_b32_e64 v73, v73, 0, s[0:1]
	s_and_b64 s[0:1], s[4:5], s[16:17]
	v_cndmask_b32_e64 v72, v72, 0, s[4:5]
	s_and_b64 s[4:5], s[0:1], s[18:19]
	v_cndmask_b32_e64 v71, v71, 0, s[0:1]
	s_and_b64 s[0:1], s[4:5], s[20:21]
	v_cndmask_b32_e64 v70, v70, 0, s[4:5]
	s_and_b64 s[4:5], s[0:1], s[22:23]
	v_cndmask_b32_e64 v69, v69, 0, s[0:1]
	s_and_b64 s[0:1], s[4:5], s[24:25]
	v_cndmask_b32_e64 v68, v68, 0, s[4:5]
	s_and_b64 s[4:5], s[0:1], s[26:27]
	v_cndmask_b32_e64 v67, v67, 0, s[0:1]
	s_and_b64 s[0:1], s[4:5], s[28:29]
	v_cndmask_b32_e64 v66, v66, 0, s[4:5]
	s_and_b64 s[4:5], s[0:1], s[30:31]
	v_cndmask_b32_e64 v64, v64, 0, s[4:5]
	v_cndmask_b32_e64 v65, v65, 0, s[0:1]
	s_add_i32 s0, 0, 0x1c000
	v_cvt_pk_bf16_f32 v148, v64, v65
	v_add_u32_e32 v64, s0, v198
	v_add_u32_e32 v202, v64, v196
	v_cndmask_b32_e64 v79, v79, 0, vcc
	v_cvt_pk_bf16_f32 v149, v66, v67
	v_cvt_pk_bf16_f32 v150, v68, v69
	v_cvt_pk_bf16_f32 v151, v70, v71
	v_cvt_pk_bf16_f32 v144, v72, v73
	v_cvt_pk_bf16_f32 v145, v74, v75
	v_cvt_pk_bf16_f32 v146, v76, v77
	v_cvt_pk_bf16_f32 v147, v78, v79
	v_add_u32_e32 v203, v64, v197
	v_add_u32_e32 v204, v64, v199
	v_add_u32_e32 v200, v64, v200
	ds_read_b128 v[64:67], v202
	ds_read_b128 v[196:199], v203
	ds_read_b128 v[246:249], v204
	ds_read_b128 v[250:253], v200
	s_waitcnt lgkmcnt(3)
	v_mfma_f32_32x32x16_bf16 v[64:79], v[64:67], v[140:143], 0
	v_cmp_gt_i32_e32 vcc, 59, v201
	v_cmp_gt_i32_e64 s[0:1], 58, v201
	v_cmp_gt_i32_e64 s[4:5], 57, v201
	s_and_b64 s[0:1], vcc, s[0:1]
	v_cmp_gt_i32_e64 s[6:7], 56, v201
	v_cmp_gt_i32_e64 s[8:9], 51, v201
	v_cmp_gt_i32_e64 s[10:11], 50, v201
	s_waitcnt lgkmcnt(2)
	v_mfma_f32_32x32x16_bf16 v[64:79], v[196:199], v[136:139], v[64:79]
	ds_read_b128 v[196:199], v202 offset:128
	v_cmp_gt_i32_e64 s[12:13], 49, v201
	v_cmp_gt_i32_e64 s[14:15], 48, v201
	v_cmp_gt_i32_e64 s[16:17], 43, v201
	v_cmp_gt_i32_e64 s[18:19], 42, v201
	v_cmp_gt_i32_e64 s[20:21], 41, v201
	v_cmp_gt_i32_e64 s[22:23], 40, v201
	s_waitcnt lgkmcnt(2)
	v_mfma_f32_32x32x16_bf16 v[64:79], v[246:249], v[132:135], v[64:79]
	ds_read_b128 v[246:249], v203 offset:128
	v_cmp_gt_i32_e64 s[24:25], 35, v201
	v_cmp_gt_i32_e64 s[26:27], 34, v201
	v_cmp_gt_i32_e64 s[28:29], 33, v201
	v_cmp_gt_i32_e64 s[30:31], 32, v201
	v_permlane32_swap_b32_e32 v148, v150
	s_waitcnt lgkmcnt(2)
	v_mfma_f32_32x32x16_bf16 v[64:79], v[250:253], v[128:131], v[64:79]
	ds_read_b128 v[250:253], v204 offset:128
	v_permlane32_swap_b32_e32 v149, v151
	v_permlane32_swap_b32_e32 v144, v146
	v_permlane32_swap_b32_e32 v145, v147
	s_waitcnt lgkmcnt(2)
	v_mfma_f32_32x32x16_bf16 v[64:79], v[196:199], v[124:127], v[64:79]
	ds_read_b128 v[196:199], v200 offset:128
	s_waitcnt lgkmcnt(2)
	v_mfma_f32_32x32x16_bf16 v[64:79], v[246:249], v[120:123], v[64:79]
	ds_read_b128 v[246:249], v202 offset:256
	s_waitcnt lgkmcnt(2)
	v_mfma_f32_32x32x16_bf16 v[64:79], v[250:253], v[116:119], v[64:79]
	ds_read_b128 v[250:253], v203 offset:256
	s_waitcnt lgkmcnt(2)
	v_mfma_f32_32x32x16_bf16 v[64:79], v[196:199], v[112:115], v[64:79]
	ds_read_b128 v[196:199], v204 offset:256
	s_waitcnt lgkmcnt(2)
	v_mfma_f32_32x32x16_bf16 v[64:79], v[246:249], v[108:111], v[64:79]
	ds_read_b128 v[246:249], v200 offset:256
	s_waitcnt lgkmcnt(2)
	v_mfma_f32_32x32x16_bf16 v[64:79], v[250:253], v[104:107], v[64:79]
	ds_read_b128 v[250:253], v202 offset:384
	s_waitcnt lgkmcnt(2)
	v_mfma_f32_32x32x16_bf16 v[64:79], v[196:199], v[100:103], v[64:79]
	ds_read_b128 v[196:199], v203 offset:384
	s_waitcnt lgkmcnt(2)
	v_mfma_f32_32x32x16_bf16 v[64:79], v[246:249], v[96:99], v[64:79]
	ds_read_b128 v[246:249], v204 offset:384
	s_waitcnt lgkmcnt(2)
	v_mfma_f32_32x32x16_bf16 v[64:79], v[250:253], v[92:95], v[64:79]
	ds_read_b128 v[250:253], v200 offset:384
	s_waitcnt lgkmcnt(2)
	v_mfma_f32_32x32x16_bf16 v[64:79], v[196:199], v[88:91], v[64:79]
	s_waitcnt lgkmcnt(1)
	v_mfma_f32_32x32x16_bf16 v[64:79], v[246:249], v[84:87], v[64:79]
	s_waitcnt lgkmcnt(0)
	v_mfma_f32_32x32x16_bf16 v[64:79], v[250:253], v[80:83], v[64:79]


; __device__ __forceinline__ void ret_block(const bf16_t* __restrict__ proj, const bf16_t* __restrict__ state, bf16_t* __restrict__ mixed, int b, int h, int qb, char* lds) {
;     ...
;             { f32x16 p; qkt1<16, 512>(p, K_lds + buf * SHM + 32 * 512, r32, hi, qr);
;               if (diag) {
; #pragma unroll
;                   for (int r = 0; r < 16; ++r) { const int C = (r & 3) + 8 * (r >> 2) + 32; if (dq - C < 0) p[r] = 0.f; } }
;               FA_PK4(p, 0, pa2); FA_PK4(p, 8, pa3); }
;             pv_tile<8192, 4096>(o, vbV + buf * SHM, pa0, pa1, pa2, pa3);
	s_nop 11
	v_cndmask_b32_e64 v78, v78, 0, s[0:1]
	s_and_b64 s[0:1], s[0:1], s[4:5]
	s_and_b64 s[4:5], s[0:1], s[6:7]
	v_cndmask_b32_e64 v77, v77, 0, s[0:1]
	s_and_b64 s[0:1], s[4:5], s[8:9]
	v_cndmask_b32_e64 v76, v76, 0, s[4:5]
	s_and_b64 s[4:5], s[0:1], s[10:11]
	v_cndmask_b32_e64 v75, v75, 0, s[0:1]
	s_and_b64 s[0:1], s[4:5], s[12:13]
	v_cndmask_b32_e64 v74, v74, 0, s[4:5]
	s_and_b64 s[4:5], s[0:1], s[14:15]
	v_cndmask_b32_e64 v73, v73, 0, s[0:1]
	s_and_b64 s[0:1], s[4:5], s[16:17]
	v_cndmask_b32_e64 v72, v72, 0, s[4:5]
	s_and_b64 s[4:5], s[0:1], s[18:19]
	v_cndmask_b32_e64 v71, v71, 0, s[0:1]
	s_and_b64 s[0:1], s[4:5], s[20:21]
	v_cndmask_b32_e64 v70, v70, 0, s[4:5]
	s_and_b64 s[4:5], s[0:1], s[22:23]
	v_cndmask_b32_e64 v69, v69, 0, s[0:1]
	s_and_b64 s[0:1], s[4:5], s[24:25]
	v_cndmask_b32_e64 v68, v68, 0, s[4:5]
	s_and_b64 s[4:5], s[0:1], s[26:27]
	v_cndmask_b32_e64 v67, v67, 0, s[0:1]
	s_and_b64 s[0:1], s[4:5], s[28:29]
	v_cndmask_b32_e64 v66, v66, 0, s[4:5]
	s_and_b64 s[4:5], s[0:1], s[30:31]
	s_cmp_lg_u32 0, -1
	v_cndmask_b32_e64 v65, v65, 0, s[0:1]
	s_cselect_b32 s0, 0, 0
	v_cndmask_b32_e64 v64, v64, 0, s[4:5]
	s_add_i32 s0, s0, 0x8000
	v_cndmask_b32_e64 v79, v79, 0, vcc
	v_cvt_pk_bf16_f32 v64, v64, v65
	v_cvt_pk_bf16_f32 v65, v66, v67
	v_cvt_pk_bf16_f32 v66, v68, v69
	v_cvt_pk_bf16_f32 v67, v70, v71
	v_cvt_pk_bf16_f32 v68, v72, v73
	v_cvt_pk_bf16_f32 v69, v74, v75
	v_cvt_pk_bf16_f32 v70, v76, v77
	v_cvt_pk_bf16_f32 v71, v78, v79
	v_add_u32_e32 v208, s0, v152
	ds_read_b64_tr_b16 v[72:73], v208 offset:0
	ds_read_b64_tr_b16 v[74:75], v208 offset:0x1000
	ds_read_b64_tr_b16 v[76:77], v208 offset:0x2000
	ds_read_b64_tr_b16 v[78:79], v208 offset:0x3000
	ds_read_b64_tr_b16 v[196:197], v208 offset:0x4000
	ds_read_b64_tr_b16 v[198:199], v208 offset:0x5000
	ds_read_b64_tr_b16 v[200:201], v208 offset:0x6000
	ds_read_b64_tr_b16 v[202:203], v208 offset:0x7000
	s_waitcnt lgkmcnt(0)
	v_permlane32_swap_b32_e32 v64, v66
	v_permlane32_swap_b32_e32 v65, v67
	v_permlane32_swap_b32_e32 v68, v70
	v_permlane32_swap_b32_e32 v69, v71
	v_mfma_f32_32x32x16_bf16 v[0:15], v[148:151], v[72:75], v[0:15]
	ds_read_b64_tr_b16 v[72:73], v208 offset:0x200
	ds_read_b64_tr_b16 v[74:75], v208 offset:0x1200
	v_mfma_f32_32x32x16_bf16 v[0:15], v[144:147], v[76:79], v[0:15]
	ds_read_b64_tr_b16 v[76:77], v208 offset:0x2200
	ds_read_b64_tr_b16 v[78:79], v208 offset:0x3200
	v_mfma_f32_32x32x16_bf16 v[0:15], v[64:67], v[196:199], v[0:15]
	ds_read_b64_tr_b16 v[196:197], v208 offset:0x4200
	ds_read_b64_tr_b16 v[198:199], v208 offset:0x5200
	ds_read_b64_tr_b16 v[204:205], v208 offset:0x6200
	ds_read_b64_tr_b16 v[206:207], v208 offset:0x7200
	s_waitcnt lgkmcnt(0)
	v_mfma_f32_32x32x16_bf16 v[0:15], v[68:71], v[200:203], v[0:15]
	v_mfma_f32_32x32x16_bf16 v[16:31], v[148:151], v[72:75], v[16:31]
	ds_read_b64_tr_b16 v[72:73], v208 offset:0x400
	ds_read_b64_tr_b16 v[74:75], v208 offset:0x1400
	v_mfma_f32_32x32x16_bf16 v[16:31], v[144:147], v[76:79], v[16:31]
	ds_read_b64_tr_b16 v[76:77], v208 offset:0x2400
	ds_read_b64_tr_b16 v[78:79], v208 offset:0x3400
	v_mfma_f32_32x32x16_bf16 v[16:31], v[64:67], v[196:199], v[16:31]
	ds_read_b64_tr_b16 v[196:197], v208 offset:0x4400
	ds_read_b64_tr_b16 v[198:199], v208 offset:0x5400
	ds_read_b64_tr_b16 v[200:201], v208 offset:0x6400
	ds_read_b64_tr_b16 v[202:203], v208 offset:0x7400
	s_waitcnt lgkmcnt(0)
	v_mfma_f32_32x32x16_bf16 v[16:31], v[68:71], v[204:207], v[16:31]
	v_mfma_f32_32x32x16_bf16 v[32:47], v[148:151], v[72:75], v[32:47]
	ds_read_b64_tr_b16 v[72:73], v208 offset:0x600
	ds_read_b64_tr_b16 v[74:75], v208 offset:0x1600
	v_mfma_f32_32x32x16_bf16 v[32:47], v[144:147], v[76:79], v[32:47]
	ds_read_b64_tr_b16 v[76:77], v208 offset:0x2600
	ds_read_b64_tr_b16 v[78:79], v208 offset:0x3600
	v_mfma_f32_32x32x16_bf16 v[32:47], v[64:67], v[196:199], v[32:47]
	ds_read_b64_tr_b16 v[196:197], v208 offset:0x4600
	ds_read_b64_tr_b16 v[198:199], v208 offset:0x5600
	ds_read_b64_tr_b16 v[204:205], v208 offset:0x6600
	ds_read_b64_tr_b16 v[206:207], v208 offset:0x7600
	s_waitcnt lgkmcnt(0)
	v_mfma_f32_32x32x16_bf16 v[32:47], v[68:71], v[200:203], v[32:47]
	v_mfma_f32_32x32x16_bf16 v[48:63], v[148:151], v[72:75], v[48:63]
	v_mfma_f32_32x32x16_bf16 v[48:63], v[144:147], v[76:79], v[48:63]
	v_mfma_f32_32x32x16_bf16 v[48:63], v[64:67], v[196:199], v[48:63]
	v_mfma_f32_32x32x16_bf16 v[48:63], v[68:71], v[204:207], v[48:63]
